# GLA chain: q_in / k_in LDS images at a 288-B row pitch (272 B made every ds_read_b128 fragment read 2-way bank conflicted); other GLA images only moved
# baseline (speedup 1.0000x reference)
; #define LAS __attribute__((address_space(3)))
; __global__ void __launch_bounds__(512, 2) fwd_megakernel(Params p) {
;     ...
;     unsigned char* ws = p.ws;
;     const int G = (int)gridDim.x, bid = (int)blockIdx.x;
;     if (threadIdx.x < 2) *(LAS unsigned*)(lds + LDS_SLOT + 16 + 4 * threadIdx.x) = 0u;
;     __syncthreads();
;     const XcdBarrier xb = xcd_barrier_post((unsigned*)(ws + OFF_BAR), (volatile LAS unsigned*)(lds + LDS_SLOT + 16));
;     if (p.ph_lo < 0) grid.sync();
;     for (int ph = p.ph_lo; ph < p.ph_hi; ++ph) {
;       for (int rep = 0; rep < ((ph == REP_PH) ? 2 : 1); ++rep) {
;         GemmDesc gd; gd.M = 0; gd.R = nullptr; gd.rope = nullptr; gd.G = G; gd.c = bid; gd.rbf = 0; gd.order = 0; gd.pad2 = 0; gd.aux = nullptr; gd.mode = 0; gd.A = nullptr; gd.Bt = nullptr; gd.C = nullptr; gd.N = 0; gd.K = 0; gd.ldc = 0;
;         switch (ph) {
;         case 0: if (EN(0)) prep_phase(p, smem); break;
;         case 1: gd.A = (const bf16_t*)(ws + OFF_B1); gd.Bt = (const bf16_t*)(ws + OFF_WIN); gd.C = ws + OFF_H; gd.rope = (const float*)(ws + OFF_ROPE); gd.aux = (float*)(ws + OFF_EB); gd.M = T_TOK; gd.N = HC; gd.K = DM; gd.ldc = HC; gd.mode = 1; break;
;         case 2:
;             if (bid < 64) { if (EN(1) && !(rep == 1 && REP_MODE == 2)) gla_item(p, bid, lds); }
;             else if (bid < 128 && !(rep == 1 && REP_MODE != 0)) { gd.A = (const bf16_t*)(ws + OFF_MEMB); gd.Bt = (const bf16_t*)(ws + OFF_WKV); gd.C = ws + OFF_MKV; gd.M = 1024; gd.N = 4096; gd.K = DM; gd.ldc = 4096; gd.mode = 0; gd.G = 64; gd.c = bid - 64; }
;             break;
;         case 3: if (EN(2)) merge_phase(p); break;
;         case 4: gd.A = (const bf16_t*)(ws + OFF_B1); gd.Bt = (const bf16_t*)(ws + OFF_WOUT); gd.C = ws + OFF_MIX4; gd.M = T_TOK; gd.N = DM; gd.K = DM; gd.ldc = DM; gd.mode = 0; break;
;         case 5: if (EN(3)) ln_phase2((const bf16_t*)(ws + OFF_MIX4), p.x, nullptr, p.ln1_g, p.ln1_b, (bf16_t*)(ws + OFF_X1B), nullptr); break;
;         case 6: gd.A = (const bf16_t*)(ws + OFF_X1B); gd.Bt = (const bf16_t*)(ws + OFF_WQ); gd.C = ws + OFF_B1; gd.M = T_TOK; gd.N = DM; gd.K = DM; gd.ldc = DM; gd.mode = 0; gd.order = 1; break;
;         case 7: break;
;         case 8: gd.A = (const bf16_t*)(ws + OFF_OC); gd.Bt = (const bf16_t*)(ws + OFF_WO); gd.C = ws + OFF_MIX8; gd.M = T_TOK; gd.N = DM; gd.K = DM; gd.ldc = DM; gd.mode = 0; break;
.LBB0_18:
	s_add_u32 s4, s92, 0x12d00000
	s_addc_u32 s5, s93, 0
	s_add_u32 s66, s92, 0x6b00000
	s_addc_u32 s67, s93, 0
	s_add_u32 s68, s92, 0x8100000
	s_addc_u32 s69, s93, 0
	s_lshl_b32 s35, s34, 9
	s_lshl_b32 s70, s60, 9
	s_add_u32 s54, s92, 0x4000000
	s_addc_u32 s55, s93, 0
	s_add_u32 s22, s92, 0x11100000
	s_addc_u32 s23, s93, 0
	s_add_u32 s64, s92, 0x19100000
	s_addc_u32 s65, s93, 0
	s_lshl_b32 s11, s34, 3
	v_writelane_b32 v251, s4, 10
	s_cmp_lg_u64 s[92:93], 0
	s_load_dwordx16 s[36:51], s[0:1], 0x40
	v_writelane_b32 v251, s5, 11
	s_cselect_b64 s[4:5], -1, 0
	v_writelane_b32 v251, s4, 12
	s_load_dwordx16 s[72:87], s[0:1], 0x0
	v_mbcnt_lo_u32_b32 v0, -1, 0
	v_writelane_b32 v251, s5, 13
	s_lshl_b32 s4, s60, 3
	s_cmpk_lt_i32 s34, 0x560
	v_writelane_b32 v251, s4, 14
	s_cselect_b64 s[4:5], -1, 0
	v_writelane_b32 v251, s4, 15
	s_lshl_b32 s14, s34, 6
	s_ashr_i32 s6, s34, 5
	v_writelane_b32 v251, s5, 16
	s_and_b32 s4, s14, 0x7c0
	v_writelane_b32 v251, s4, 17
	s_lshl_b32 s4, s6, 7
	v_writelane_b32 v251, s4, 18
	s_lshl_b32 s4, s6, 8
	s_add_u32 s26, s92, 0xd100000
	s_addc_u32 s27, s93, 0
	v_writelane_b32 v251, s4, 19
	s_add_u32 s4, s92, 0xb800000
	s_addc_u32 s5, s93, 0
	v_writelane_b32 v251, s4, 20
	v_mbcnt_hi_u32_b32 v215, -1, v0
	v_and_b32_e32 v0, 64, v215
	v_writelane_b32 v251, s5, 21
	s_add_u32 s4, s92, 0xa000000
	s_addc_u32 s5, s93, 0
	v_writelane_b32 v251, s4, 22
	v_mov_b32_e32 v3, 0
	v_mov_b32_e32 v213, 0x3727c5ac
	v_writelane_b32 v251, s5, 23
	s_add_u32 s4, s92, 0x9800000
	s_addc_u32 s5, s93, 0
	v_writelane_b32 v251, s4, 24
	v_mov_b32_e32 v214, 1
	v_add_u32_e32 v216, 64, v0
	v_writelane_b32 v251, s5, 25
	s_add_u32 s4, s92, 0x6000000
	s_addc_u32 s5, s93, 0
	s_add_u32 s24, s92, 0x1b100000
	v_writelane_b32 v251, s4, 26
	s_addc_u32 s25, s93, 0
	v_xor_b32_e32 v217, 32, v215
	v_writelane_b32 v251, s5, 27
	s_add_u32 s4, s92, 0xcc00000
	s_addc_u32 s5, s93, 0
	v_writelane_b32 v251, s4, 28
	s_cmp_gt_i32 s34, 63
	v_xor_b32_e32 v218, 16, v215
	v_writelane_b32 v251, s5, 29
	s_cselect_b64 s[4:5], -1, 0
	v_writelane_b32 v251, s4, 30
	s_cmpk_lt_u32 s34, 0x80
	v_xor_b32_e32 v250, 1, v215
	v_writelane_b32 v251, s5, 31
	s_cselect_b64 s[4:5], -1, 0
	v_writelane_b32 v251, s4, 32
	v_mov_b32_e32 v219, 0x6600
	v_mov_b32_e32 v224, 0x8800
	v_writelane_b32 v251, s5, 33
	s_sub_i32 s4, s34, 64
	s_add_u32 s30, s92, 0xc400000
	s_addc_u32 s31, s93, 0
	v_writelane_b32 v251, s4, 34
	s_add_u32 s4, s92, 0xa800000
	s_addc_u32 s5, s93, 0
	v_writelane_b32 v251, s4, 35
	v_mov_b32_e32 v225, 0xaa00
	v_mov_b32_e32 v226, 0xcc00
	v_writelane_b32 v251, s5, 36
	s_add_u32 s4, s92, 0xc000000
	s_addc_u32 s5, s93, 0
	v_writelane_b32 v251, s4, 37
	v_mov_b32_e32 v227, 0xee00
	v_mov_b32_e32 v228, 0xf149f2ca
	v_writelane_b32 v251, s5, 38
	s_lshl_b32 s5, s34, 8
	s_and_b32 s16, s5, 0xfffff000
	s_bfe_u32 s4, s34, 0x20002
	s_ashr_i32 s17, s16, 31
	s_mul_i32 s7, s16, 0x3000
	s_mul_hi_i32 s5, s16, 0x3000
	s_add_u32 s7, s26, s7
	s_addc_u32 s5, s27, s5
	s_lshl_b32 s8, s4, 8
	s_add_u32 s18, s7, s8
	s_addc_u32 s19, s5, 0
	s_lshl_b32 s9, s4, 9
	s_add_u32 s4, s7, s9
	s_addc_u32 s5, s5, 0
	s_lshl_b32 s10, s34, 7
	s_and_b32 s7, s10, 0x180
	v_writelane_b32 v251, s18, 39
	s_add_u32 s4, s4, s7
	s_addc_u32 s5, s5, 0
	v_writelane_b32 v251, s19, 40
	v_writelane_b32 v251, s4, 41
	s_add_u32 s18, s92, 0x1d100000
	s_addc_u32 s19, s93, 0
	v_writelane_b32 v251, s5, 42
	s_mov_b32 s4, s16
	v_writelane_b32 v251, s4, 43
	s_mov_b32 s98, 0xbfb8aa3b
	s_movk_i32 s99, 0x110
	v_writelane_b32 v251, s5, 44
	s_lshl_b64 s[4:5], s[16:17], 10
	s_add_u32 s4, s18, s4
	v_writelane_b32 v251, s18, 45
	s_addc_u32 s5, s19, s5
	s_add_u32 s4, s4, s8
	v_writelane_b32 v251, s19, 46
	v_writelane_b32 v251, s4, 47
	s_addc_u32 s4, s5, 0
	v_writelane_b32 v251, s4, 48
	s_add_u32 s4, s64, s9
	s_addc_u32 s5, s65, 0
	s_add_u32 s4, s4, s7
	v_writelane_b32 v251, s4, 49
	s_addc_u32 s4, s5, 0
	v_writelane_b32 v251, s4, 50
	s_add_u32 s4, s92, 0x8000000
	s_addc_u32 s5, s93, 0
	v_writelane_b32 v251, s4, 51
	s_mov_b32 s19, 0
	s_mov_b32 s52, 0x3d8293ee
	v_writelane_b32 v251, s5, 52
	s_add_u32 s4, s92, 0xce01000
	s_addc_u32 s5, s93, 0
	v_writelane_b32 v251, s4, 53
	s_cmp_eq_u32 s34, 0
	s_movk_i32 s33, 0x7f
	v_writelane_b32 v251, s5, 54
	s_cselect_b64 s[4:5], -1, 0
	v_writelane_b32 v251, s4, 55
	s_movk_i32 s29, 0x81
	s_movk_i32 s28, 0xff7e
	v_writelane_b32 v251, s5, 56
	s_add_u32 s4, s92, 0xce00000
	s_addc_u32 s5, s93, 0
	v_writelane_b32 v251, s4, 57
	s_cmpk_lt_i32 s34, 0x100
	s_movk_i32 s53, 0x7e
	v_writelane_b32 v251, s5, 58
	s_cselect_b64 s[4:5], -1, 0
	v_writelane_b32 v251, s4, 59
	s_mov_b64 s[20:21], 0x80
	s_nop 0
	v_writelane_b32 v251, s5, 60
	s_lshl_b32 s4, s34, 1
	s_add_i32 s5, s4, 16
	s_and_b32 s5, s5, 48
	v_writelane_b32 v251, s5, 61
	s_and_b32 s5, s4, 48
	s_add_i32 s4, s4, 48
	s_and_b32 s4, s4, 48
	v_writelane_b32 v251, s4, 62
	s_xor_b32 s4, s5, 32
	s_cmpk_lt_i32 s34, 0x500
	v_writelane_b32 v251, s5, 63
	v_writelane_b32 v252, s4, 0
	s_cselect_b64 s[4:5], -1, 0
	v_writelane_b32 v252, s4, 1
	s_nop 1
	v_writelane_b32 v252, s5, 2
	s_add_i32 s4, s34, 0x200
	s_cmpk_lt_i32 s34, 0x300
	s_cselect_b32 s7, s34, s4
	s_cmpk_gt_i32 s7, 0x2ff
	s_cselect_b64 s[4:5], -1, 0
	v_writelane_b32 v252, s4, 3
	s_cmpk_gt_u32 s7, 0x3ff
	s_nop 0
	v_writelane_b32 v252, s5, 4
	s_cselect_b64 s[4:5], -1, 0
	s_lshl_b32 s8, s7, 3
	v_writelane_b32 v252, s4, 5
	s_cmpk_lt_u32 s7, 0x500
	s_nop 0
	v_writelane_b32 v252, s5, 6
	s_cselect_b64 s[4:5], -1, 0
	s_and_b32 s9, s8, 0x1f00
	s_add_i32 s13, s9, 0xffffe800
	v_writelane_b32 v252, s13, 7
	s_addk_i32 s9, 0xe880
	v_writelane_b32 v252, s9, 8
	s_and_b32 s9, s8, 0x3f00
	s_and_b32 s15, s8, 0xffffff00
	s_cmpk_gt_i32 s15, 0xbff
	s_cselect_b32 s8, 16, 0
; __device__ __forceinline__ WtDesc wt_decode(const Params& p, int grp, int tl) {
;     WtDesc d; unsigned char* ws = p.ws;
;     if (grp == 0) {
;         if (tl < 768)       { const int kt = tl & 31, nt = tl >> 5; const int n0 = nt * 256, s0 = n0 + (n0 >= 3072 ? 16 : 0); d.W = p.w_in; d.ldw = 6160; d.k0 = kt * 64; d.ns0 = s0; d.ns1 = s0 + 128; d.Bt = (bf16_t*)(ws + OFF_WIN); d.K = 2048; d.n0dst = n0; }
; __device__ __forceinline__ void xcd_barrier_complete(unsigned* bar, unsigned x, unsigned& nloc, unsigned& nx) {
;     const unsigned G = gridDim.x * gridDim.y * gridDim.z;
;     unsigned sum, cnt, mine, sp = 0u;
;     for (;;) {
;         sum = 0u; cnt = 0u; mine = 0u;
; #pragma unroll
;         for (unsigned j = 0; j < 16; ++j) { const unsigned c = xb_ld(&bar[XB_XCNT(j)]); sum += c; cnt += (c > 0u) ? 1u : 0u; mine = (j == x) ? c : mine; }
;         if (sum == G) break;
;         __builtin_amdgcn_s_sleep(1);
;         if ((++sp & 255u) == 0u) { if (xb_ld(&bar[XB_TMO])) break; if (sp > XB_SPIN_CAP) { atomicAdd(&bar[XB_TMO], 1u); break; } }
;     }
;     nloc = mine > 0u ? mine : 1u; nx = cnt > 0u ? cnt : 1u;
; }
; __device__ __forceinline__ void xcd_barrier(const XcdBarrier& b) {
;     asm volatile("s_waitcnt vmcnt(0)" ::: "memory");
;     __syncthreads();
;     if (threadIdx.x == 0) {
;         unsigned* bar = b.bar;
;         __builtin_amdgcn_s_waitcnt(0);
;         unsigned nloc = b.st[0], nx = b.st[1];
;         if (nloc == 0u) { xcd_barrier_complete(bar, b.x, nloc, nx); b.st[0] = nloc; b.st[1] = nx; }
;         const unsigned old = xb_add(&bar[XB_XSUB(b.x)], 1u);
;         const unsigned gen = old / nloc;
;         if (old + 1u == (gen + 1u) * nloc) {
;             __builtin_amdgcn_fence(__ATOMIC_RELEASE, "agent");
;             asm volatile("s_waitcnt vmcnt(0)" ::: "memory");
;             const unsigned og = xb_add(&bar[XB_TOP], 1u);
;             const unsigned tg = og / nx;
;             if (og + 1u == (tg + 1u) * nx) xb_add(&bar[XB_TOPGEN], 1u);
;             else XB_SPIN(xb_ld(&bar[XB_TOPGEN]) == tg, bar);
;             __builtin_amdgcn_fence(__ATOMIC_ACQUIRE, "agent");
;             xb_add(&bar[XB_XGEN(b.x)], 1u);
;             asm volatile("s_waitcnt vmcnt(0)" ::: "memory");
;         } else {
;             XB_SPIN(xb_ld(&bar[XB_XGEN(b.x)]) == gen, bar);
	v_writelane_b32 v252, s11, 9
	s_and_b32 s11, s11, 56
	s_add_i32 s11, s11, s6
	s_lshl_b32 s6, s11, 3
	s_lshl_b32 s13, s34, 2
	s_and_b32 s6, s6, 0xffffff80
	s_and_b32 s13, s13, 0x60
	s_or_b32 s13, s6, s13
	s_lshl_b32 s6, s7, 6
	v_writelane_b32 v252, s15, 10
	s_and_b32 s6, s6, 0x7c0
	v_writelane_b32 v252, s6, 11
	s_lshl_b32 s6, s11, 4
	s_and_b32 s6, s6, 0xffffff00
	s_or_b32 s15, s8, s15
	s_ashr_i32 s7, s6, 31
	s_lshl_b32 s8, s11, 1
	s_lshl_b64 s[6:7], s[6:7], 13
	s_or_b32 s11, s15, 0x80
	s_add_u32 s6, s30, s6
	s_addc_u32 s7, s31, s7
	s_and_b32 s10, s10, 0xc00
	v_writelane_b32 v252, s15, 12
	s_add_u32 s6, s6, s10
	v_writelane_b32 v252, s11, 13
	s_addc_u32 s7, s7, 0
	v_writelane_b32 v252, s6, 14
	s_nop 1
	v_writelane_b32 v252, s7, 15
	s_and_b32 s6, s8, 30
	s_or_b32 s10, s13, s6
	s_cmpk_gt_i32 s34, 0xbf
	s_cselect_b64 s[6:7], -1, 0
	v_writelane_b32 v252, s6, 16
	s_cmpk_lt_u32 s34, 0x370
	s_nop 0
	v_writelane_b32 v252, s7, 17
	s_cselect_b64 s[6:7], -1, 0
	v_writelane_b32 v252, s6, 18
	s_nop 1
	v_writelane_b32 v252, s7, 19
	s_add_i32 s6, s34, 0xff40
	s_and_b32 s7, s6, 0xffff
	s_mul_i32 s7, s7, 0xbe83
	s_lshr_b32 s7, s7, 22
	s_mul_i32 s8, s7, 0x56
	s_sub_i32 s6, s6, s8
	s_lshl_b32 s6, s6, 6
	s_and_b32 s6, s6, 0xffc0
	v_writelane_b32 v252, s6, 20
	s_lshl_b32 s6, s7, 8
	v_writelane_b32 v252, s6, 21
	s_bitset1_b32 s6, 7
	v_writelane_b32 v252, s6, 22
	s_add_u32 s6, s92, 0x1f400200
	s_addc_u32 s7, s93, 0
	v_writelane_b32 v252, s6, 23
	s_nop 1
	v_writelane_b32 v252, s7, 24
	s_add_u32 s6, s92, 0x1f400400
	s_addc_u32 s7, s93, 0
	v_writelane_b32 v252, s6, 25
	s_nop 1
	v_writelane_b32 v252, s7, 26
	s_add_u32 s6, s92, 0x1f400500
	s_addc_u32 s7, s93, 0
	v_writelane_b32 v252, s6, 27
	s_nop 1
	v_writelane_b32 v252, s7, 28
	s_add_u32 s6, s92, 0x1f400600
	s_addc_u32 s7, s93, 0
	v_writelane_b32 v252, s6, 29
	s_nop 1
	v_writelane_b32 v252, s7, 30
	s_add_u32 s6, s92, 0x1f400700
	s_addc_u32 s7, s93, 0
	v_writelane_b32 v252, s6, 31
	s_nop 1
	v_writelane_b32 v252, s7, 32
	s_add_u32 s6, s92, 0x1f400800
	s_addc_u32 s7, s93, 0
	v_writelane_b32 v252, s6, 33
	s_nop 1
	v_writelane_b32 v252, s7, 34
	s_add_u32 s6, s92, 0x1f400900
	s_addc_u32 s7, s93, 0
	v_writelane_b32 v252, s6, 35
	s_nop 1
	v_writelane_b32 v252, s7, 36
	s_add_u32 s6, s92, 0x1f400a00
	s_addc_u32 s7, s93, 0
	v_writelane_b32 v252, s6, 37
	s_nop 1
	v_writelane_b32 v252, s7, 38
	s_add_u32 s6, s92, 0x1f400b00
	s_addc_u32 s7, s93, 0
	v_writelane_b32 v252, s6, 39
	s_nop 1
	v_writelane_b32 v252, s7, 40
	s_add_u32 s6, s92, 0x1f400c00
	s_addc_u32 s7, s93, 0
	v_writelane_b32 v252, s6, 41
	s_nop 1
	v_writelane_b32 v252, s7, 42
	s_add_u32 s6, s92, 0x1f400d00
	s_addc_u32 s7, s93, 0
	v_writelane_b32 v252, s6, 43
	s_nop 1
	v_writelane_b32 v252, s7, 44
	s_add_u32 s6, s92, 0x1f400e00
	s_addc_u32 s7, s93, 0
	v_writelane_b32 v252, s6, 45
	s_nop 1
	v_writelane_b32 v252, s7, 46
	s_add_u32 s6, s92, 0x1f400f00
	s_addc_u32 s7, s93, 0
	v_writelane_b32 v252, s6, 47
	s_nop 1
	v_writelane_b32 v252, s7, 48
	s_add_u32 s6, s92, 0x1f401000
	s_addc_u32 s7, s93, 0
	v_writelane_b32 v252, s6, 49
	s_nop 1
	v_writelane_b32 v252, s7, 50
	s_add_u32 s6, s92, 0x1f401100
	s_addc_u32 s7, s93, 0
	v_writelane_b32 v252, s6, 51
	s_nop 1
	v_writelane_b32 v252, s7, 52
	s_add_u32 s6, s92, 0x1f401200
	s_addc_u32 s7, s93, 0
	v_writelane_b32 v252, s6, 53
	s_nop 1
	v_writelane_b32 v252, s7, 54
	s_add_u32 s6, s92, 0x1f401300
	s_addc_u32 s7, s93, 0
	v_writelane_b32 v252, s6, 55
	s_cmp_eq_u32 s12, 15
	s_nop 0
	v_writelane_b32 v252, s7, 56
	s_cselect_b64 s[6:7], -1, 0
	v_writelane_b32 v252, s6, 57
	s_cmp_eq_u32 s12, 14
	s_nop 0
	v_writelane_b32 v252, s7, 58
	s_cselect_b64 s[6:7], -1, 0
	v_writelane_b32 v252, s6, 59
	s_cmp_eq_u32 s12, 13
	s_nop 0
	v_writelane_b32 v252, s7, 60
	s_cselect_b64 s[6:7], -1, 0
	v_writelane_b32 v252, s6, 61
	s_cmp_eq_u32 s12, 12
	s_nop 0
	v_writelane_b32 v252, s7, 62
	s_cselect_b64 s[6:7], -1, 0
	v_writelane_b32 v252, s6, 63
	s_cmp_eq_u32 s12, 11
	s_nop 0
	v_writelane_b32 v253, s7, 0
	s_cselect_b64 s[6:7], -1, 0
	v_writelane_b32 v253, s6, 1
	s_cmp_eq_u32 s12, 10
	s_nop 0
	v_writelane_b32 v253, s7, 2
	s_cselect_b64 s[6:7], -1, 0
	v_writelane_b32 v253, s6, 3
	s_cmp_eq_u32 s12, 9
	s_nop 0
	v_writelane_b32 v253, s7, 4
	s_cselect_b64 s[6:7], -1, 0
	v_writelane_b32 v253, s6, 5
	s_cmp_eq_u32 s12, 8
	s_nop 0
	v_writelane_b32 v253, s7, 6
	s_cselect_b64 s[6:7], -1, 0
	v_writelane_b32 v253, s6, 7
	s_cmp_eq_u32 s12, 7
	s_nop 0
	v_writelane_b32 v253, s7, 8
	s_cselect_b64 s[6:7], -1, 0
	v_writelane_b32 v253, s6, 9
	s_cmp_eq_u32 s12, 6
	s_nop 0
	v_writelane_b32 v253, s7, 10
	s_cselect_b64 s[6:7], -1, 0
	v_writelane_b32 v253, s6, 11
	s_cmp_eq_u32 s12, 5
	s_nop 0
	v_writelane_b32 v253, s7, 12
	s_cselect_b64 s[6:7], -1, 0
	v_writelane_b32 v253, s6, 13
	s_cmp_eq_u32 s12, 4
	s_nop 0
	v_writelane_b32 v253, s7, 14
	s_cselect_b64 s[6:7], -1, 0
	v_writelane_b32 v253, s6, 15
	s_cmp_eq_u32 s12, 3
	s_nop 0
	v_writelane_b32 v253, s7, 16
	s_cselect_b64 s[6:7], -1, 0
	v_writelane_b32 v253, s6, 17
	s_cmp_eq_u32 s12, 2
	s_nop 0
	v_writelane_b32 v253, s7, 18
	s_cselect_b64 s[6:7], -1, 0
	v_writelane_b32 v253, s6, 19
	s_cmp_eq_u32 s12, 1
	s_nop 0
	v_writelane_b32 v253, s7, 20
	s_cselect_b64 s[6:7], -1, 0
	v_writelane_b32 v253, s6, 21
	s_cmp_eq_u32 s12, 0
	s_nop 0
	v_writelane_b32 v253, s7, 22
	s_cselect_b64 s[6:7], -1, 0
	v_writelane_b32 v253, s6, 23
	s_nop 1
	v_writelane_b32 v253, s7, 24
	s_lshl_b32 s6, s12, 8
	s_add_u32 s2, s2, s6
	s_addc_u32 s3, s3, 0
	s_add_u32 s6, s2, 0x1400
	s_addc_u32 s7, s3, 0
	v_writelane_b32 v253, s6, 25
	s_add_u32 s2, s2, 0x2400
	s_addc_u32 s3, s3, 0
	v_writelane_b32 v253, s7, 26
	v_writelane_b32 v253, s2, 27
	s_nop 1
	v_writelane_b32 v253, s3, 28
	s_add_u32 s2, s92, 0x1f403400
	s_addc_u32 s3, s93, 0
	v_writelane_b32 v253, s2, 29
	s_nop 1
	v_writelane_b32 v253, s3, 30
	s_add_u32 s2, s92, 0x1f403500
	s_addc_u32 s3, s93, 0
	v_writelane_b32 v253, s2, 31
	s_nop 1
	v_writelane_b32 v253, s3, 32
	s_and_b64 s[2:3], s[4:5], exec
	s_waitcnt lgkmcnt(0)
; #define LAS __attribute__((address_space(3)))
; __device__ __forceinline__ int opaque_tid() { int t = (int)threadIdx.x; asm volatile("" : "+v"(t)); return t; }
; __device__ void gla_item(const Params& p, int item, LAS unsigned char* lds) {
;     const int tid = opaque_tid(), lane = tid & 63, w = __builtin_amdgcn_readfirstlane(tid >> 6), idx = lane & 15, g = lane >> 4;
;     const int b = item >> 4, hh = (item >> 2) & 3, sl = item & 3;
;     constexpr int QS0 = 0, KS = 34816, VS0 = 52224, ST0 = 70656, AS = 105472;
;     const unsigned lbase = (unsigned)(size_t)lds;
;     unsigned char* ws = p.ws;
;     const bf16_t* h = (const bf16_t*)(ws + OFF_H);
;     bf16_t* og = (bf16_t*)(ws + OFF_OG);
;     const int t = tid >> 3, cgp = tid & 7;
;     const bf16_t* hq = h + (size_t)(b * SEQ) * HC + hh * 128 + cgp * 16;
;     const bf16_t* hv = h + (size_t)(b * SEQ) * HC + 1024 + hh * 256 + sl * 64 + cgp * 8;
;     const bf16_t* pdec = (const bf16_t*)(ws + OFF_EB) + (size_t)(b * SEQ) * 512 + hh * 128 + 16 * w + 4 * g;
;     { unsigned zz = 0u; asm volatile("" : "+v"(zz)); const u32x4 zv = {zz, zz, zz, zz};
;       for (int i = tid; i < 17408 / 16; i += 512) *(LAS u32x4*)(lds + ST0 + i * 16) = zv; }
;     f32x4 S[4];
; #pragma unroll
;     for (int i = 0; i < 4; ++i) S[i] = (f32x4){0.f, 0.f, 0.f, 0.f};
;     const int jt = w >> 1, it0 = 2 * (w & 1);
;     GlaRegs RA, RB;
;     gla_load(RA, 0, t, hq, hv, pdec); gla_load(RB, 1, t, hq, hv, pdec);
;     for (int n2 = 0; n2 < 64; n2 += 2) {
; #pragma unroll
;       for (int par = 0; par < 2; ++par) {
;         const int n = n2 + par;
;         GlaRegs& R = par ? RB : RA;
;         const int qs = QS0 + par * 17408, vs = VS0 + par * 9216, stc = ST0 + par * 17408, stn = ST0 + (par ^ 1) * 17408;
; __device__ __forceinline__ void xcd_barrier_complete(unsigned* bar, unsigned x, unsigned& nloc, unsigned& nx) {
;     const unsigned G = gridDim.x * gridDim.y * gridDim.z;
	s_cselect_b32 s3, s41, s43
	v_writelane_b32 v253, s36, 33
	s_cselect_b32 s2, s40, s42
	s_nop 0
	v_writelane_b32 v253, s37, 34
	v_writelane_b32 v253, s38, 35
	v_writelane_b32 v253, s39, 36
	v_writelane_b32 v253, s40, 37
	v_writelane_b32 v253, s41, 38
	v_writelane_b32 v253, s42, 39
	v_writelane_b32 v253, s43, 40
	v_writelane_b32 v253, s44, 41
	v_writelane_b32 v253, s45, 42
	v_writelane_b32 v253, s46, 43
	v_writelane_b32 v253, s47, 44
	v_writelane_b32 v253, s48, 45
	v_writelane_b32 v253, s49, 46
	v_writelane_b32 v253, s50, 47
	v_writelane_b32 v253, s51, 48
	v_writelane_b32 v253, s2, 49
	s_mov_b32 s44, 0x6dc9c883
	s_mov_b32 s45, 0x3fc45f30
	v_writelane_b32 v253, s3, 50
	s_mov_b32 s3, 0xa000000
	s_cselect_b32 s18, s3, 0xa800000
	s_movk_i32 s3, 0x800
	s_movk_i32 s2, 0xe000
	s_cselect_b32 s6, s3, 0x1000
	s_cselect_b32 s2, s2, 0xffffd800
	v_writelane_b32 v253, s6, 51
	s_add_i32 s2, s9, s2
	s_movk_i32 s48, 0x3000
	v_writelane_b32 v253, s7, 52
	v_writelane_b32 v253, s2, 53
	s_and_b64 s[2:3], s[4:5], exec
	s_movk_i32 s2, 0xe080
	s_cselect_b32 s2, s2, 0xffffd880
	s_add_i32 s2, s9, s2
	v_writelane_b32 v253, s2, 54
	s_load_dword s2, s[0:1], 0xc8
	s_mov_b32 s49, 0xf149f2ca
	s_waitcnt lgkmcnt(0)
	s_mul_i32 s2, s61, s2
	s_mul_i32 s2, s2, s60
	v_writelane_b32 v253, s2, 55
	s_add_i32 s2, s34, s60
	s_lshl_b32 s2, s2, 6
	v_writelane_b32 v253, s2, 56
	s_lshl_b32 s2, s60, 6
	v_writelane_b32 v253, s2, 57
	v_writelane_b32 v253, s10, 58
	s_lshl_b32 s2, s10, 4
	v_writelane_b32 v253, s2, 59
	s_add_u32 s2, s92, 0xd100080
	s_addc_u32 s3, s93, 0
	v_writelane_b32 v253, s2, 60
	s_add_i32 s38, 0, 0x22000
	s_mov_b32 s61, 0x3fb8aa3b
	v_writelane_b32 v253, s3, 61
	v_writelane_b32 v253, s14, 62
	s_add_i32 s2, s14, 0x12800
	v_writelane_b32 v253, s2, 63
	s_add_i32 s2, s34, 0x4e0
	v_writelane_b32 v254, s2, 0
	s_add_i32 s2, 0, 0x12000
	v_writelane_b32 v254, s2, 1
	s_add_i32 s2, 0, 0x9000
	v_writelane_b32 v254, s2, 2
	s_add_i32 s2, 0, 0x1a800
	v_writelane_b32 v254, s2, 3
	s_add_i32 s2, 0, 0xd800
	v_writelane_b32 v254, s2, 4
	s_add_i32 s2, 0, 0x16400
	v_writelane_b32 v254, s2, 5
	s_add_i32 s2, 0, 0xfc00
	v_writelane_b32 v254, s2, 6
	s_add_i32 s2, 0, 0x22010
	v_writelane_b32 v254, s2, 7
	s_add_i32 s2, 0, 0x22014
	v_writelane_b32 v254, s2, 8
	v_writelane_b32 v254, s18, 9
	s_add_i32 s14, 0, 0x11080
	s_nop 0
	v_writelane_b32 v254, s19, 10
	v_writelane_b32 v254, s22, 11
	s_nop 1
	v_writelane_b32 v254, s23, 12
	v_writelane_b32 v254, s64, 13
	s_nop 1
	v_writelane_b32 v254, s65, 14
	v_writelane_b32 v254, s26, 15
	s_nop 1
	v_writelane_b32 v254, s27, 16
	v_writelane_b32 v254, s24, 17
	s_nop 1
	v_writelane_b32 v254, s25, 18
	v_writelane_b32 v254, s38, 19
	v_writelane_b32 v254, s34, 20
	v_writelane_b32 v254, s60, 21
	s_nop 1
	v_writelane_b32 v254, s61, 22
	v_writelane_b32 v254, s62, 23
	s_nop 1
	v_writelane_b32 v254, s63, 24
	v_writelane_b32 v254, s66, 25
	s_nop 1
	v_writelane_b32 v254, s67, 26
	v_writelane_b32 v254, s68, 27
	s_nop 1
	v_writelane_b32 v254, s69, 28
	v_writelane_b32 v254, s35, 29
	v_writelane_b32 v254, s70, 30
	v_writelane_b32 v254, s54, 31
	s_nop 1
	v_writelane_b32 v254, s55, 32
	s_branch .LBB0_22

; #define LAS __attribute__((address_space(3)))
; __device__ void gla_item(const Params& p, int item, LAS unsigned char* lds) {
;     const int tid = opaque_tid(), lane = tid & 63, w = __builtin_amdgcn_readfirstlane(tid >> 6), idx = lane & 15, g = lane >> 4;
;     const int b = item >> 4, hh = (item >> 2) & 3, sl = item & 3;
;     constexpr int QS0 = 0, KS = 34816, VS0 = 52224, ST0 = 70656, AS = 105472;
;     const unsigned lbase = (unsigned)(size_t)lds;
;     unsigned char* ws = p.ws;
;     const bf16_t* h = (const bf16_t*)(ws + OFF_H);
;     bf16_t* og = (bf16_t*)(ws + OFF_OG);
;     const int t = tid >> 3, cgp = tid & 7;
;     const bf16_t* hq = h + (size_t)(b * SEQ) * HC + hh * 128 + cgp * 16;
;     const bf16_t* hv = h + (size_t)(b * SEQ) * HC + 1024 + hh * 256 + sl * 64 + cgp * 8;
;     const bf16_t* pdec = (const bf16_t*)(ws + OFF_EB) + (size_t)(b * SEQ) * 512 + hh * 128 + 16 * w + 4 * g;
;     { unsigned zz = 0u; asm volatile("" : "+v"(zz)); const u32x4 zv = {zz, zz, zz, zz};
;       for (int i = tid; i < 17408 / 16; i += 512) *(LAS u32x4*)(lds + ST0 + i * 16) = zv; }
;     f32x4 S[4];
; #pragma unroll
;     for (int i = 0; i < 4; ++i) S[i] = (f32x4){0.f, 0.f, 0.f, 0.f};
;     const int jt = w >> 1, it0 = 2 * (w & 1);
;     GlaRegs RA, RB;
;     gla_load(RA, 0, t, hq, hv, pdec); gla_load(RB, 1, t, hq, hv, pdec);
;     for (int n2 = 0; n2 < 64; n2 += 2) {
; #pragma unroll
;       for (int par = 0; par < 2; ++par) {
;         const int n = n2 + par;
;         GlaRegs& R = par ? RB : RA;
;         const int qs = QS0 + par * 17408, vs = VS0 + par * 9216, stc = ST0 + par * 17408, stn = ST0 + (par ^ 1) * 17408;
;         gla_wait(R, n2 == 0);
;         *(LAS u32x4*)(lds + qs + t * 272 + cgp * 32) = R.rq[0]; *(LAS u32x4*)(lds + qs + t * 272 + cgp * 32 + 16) = R.rq[1];
;         *(LAS u32x4*)(lds + KS + t * 272 + cgp * 32) = R.rk[0]; *(LAS u32x4*)(lds + KS + t * 272 + cgp * 32 + 16) = R.rk[1];
;         *(LAS u32x4*)(lds + vs + t * 144 + cgp * 16) = R.rv;
;         f32x4 dc; dc[0] = bflo(R.rdec.x); dc[1] = bfhi(R.rdec.x); dc[2] = bflo(R.rdec.y); dc[3] = bfhi(R.rdec.y);
;         asm volatile("" : "+v"(dc) :: "memory");
;         gla_load(R, (n + 2 < 64) ? n + 2 : 63, t, hq, hv, pdec);
;         LDS_BARRIER();
;         const unsigned kaddr = lbase + KS + (unsigned)((8 * g + (idx >> 2)) * 272 + (16 * w + 4 * (idx & 3)) * 2);
.LBB0_113:
	s_movk_i32 s32, 0x120
	s_or_b64 exec, exec, s[2:3]
	v_and_b32_e32 v0, 7, v44
	v_readlane_b32 s2, v251, 39
	v_lshlrev_b32_e32 v2, 4, v0
	v_lshlrev_b32_e32 v0, 5, v0
	v_mov_b32_e32 v1, v3
	v_readlane_b32 s3, v251, 40
	s_ashr_i32 s9, s8, 6
	v_bfe_u32 v50, v44, 4, 2
	v_lshl_add_u64 v[80:81], s[2:3], 0, v[0:1]
	v_readlane_b32 s2, v251, 41
	v_readlane_b32 s3, v251, 42
	v_ashrrev_i32_e32 v96, 3, v44
	v_lshlrev_b32_e32 v46, 3, v50
	v_lshl_add_u64 v[4:5], s[2:3], 0, v[2:3]
	s_mov_b64 s[2:3], 0x800
	v_lshl_add_u64 v[82:83], v[4:5], 0, s[2:3]
	s_lshl_b32 s2, s9, 4
	s_ashr_i32 s3, s2, 31
	s_lshl_b64 s[6:7], s[2:3], 1
	v_readlane_b32 s3, v251, 47
	s_add_u32 s6, s3, s6
	v_readlane_b32 s3, v251, 48
	s_addc_u32 s7, s3, s7
	v_mov_b32_e32 v47, v3
	v_lshl_add_u64 v[84:85], s[6:7], 0, v[46:47]
	v_mad_i64_i32 v[16:17], s[6:7], v96, s48, v[80:81]
	s_mov_b64 s[16:17], 0x400
	global_load_dwordx4 v[4:7], v[16:17], off
	v_lshl_add_u64 v[8:9], v[16:17], 0, 16
	s_mov_b64 s[22:23], 0x410
	global_load_dwordx4 v[8:11], v[8:9], off
	v_lshl_add_u64 v[12:13], v[16:17], 0, s[16:17]
	global_load_dwordx4 v[12:15], v[12:13], off
	v_lshl_add_u64 v[16:17], v[16:17], 0, s[22:23]
	v_mad_i64_i32 v[20:21], s[6:7], v96, s48, v[82:83]
	global_load_dwordx4 v[16:19], v[16:17], off
	s_mov_b64 s[12:13], 0xfc00
	global_load_dwordx4 v[20:23], v[20:21], off
	v_add_u32_e32 v1, 64, v96
	v_lshl_add_u64 v[24:25], v[84:85], 0, s[12:13]
	global_load_dwordx2 v[86:87], v[24:25], off
	v_mad_i64_i32 v[36:37], s[6:7], v1, s48, v[80:81]
	global_load_dwordx4 v[24:27], v[36:37], off
	v_lshl_add_u64 v[28:29], v[36:37], 0, 16
	global_load_dwordx4 v[28:31], v[28:29], off
	v_lshl_add_u64 v[32:33], v[36:37], 0, s[16:17]
	s_mov_b64 s[6:7], 0x1fc00
	global_load_dwordx4 v[32:35], v[32:33], off
	v_lshl_add_u64 v[36:37], v[36:37], 0, s[22:23]
	v_lshl_add_u64 v[48:49], v[84:85], 0, s[6:7]
	v_mad_i64_i32 v[40:41], s[6:7], v1, s48, v[82:83]
	global_load_dwordx4 v[36:39], v[36:37], off
	global_load_dwordx4 v[40:43], v[40:41], off
	v_lshlrev_b32_e32 v52, 2, v44
	global_load_dwordx2 v[90:91], v[48:49], off
	v_bfe_u32 v48, v44, 2, 2
	v_and_b32_e32 v52, 12, v52
	s_lshl_b32 s3, s9, 5
	v_or_b32_e32 v48, v46, v48
	v_or_b32_e32 v53, s2, v52
	s_and_b32 s9, s3, 32
	v_mul_u32_u24_e32 v49, 0x120, v48
	v_lshlrev_b32_e32 v53, 1, v53
	v_readlane_b32 s3, v254, 2
	v_and_b32_e32 v45, 15, v44
	v_lshlrev_b32_e32 v51, 2, v50
	v_add3_u32 v97, v53, s3, v49
	s_ashr_i32 s3, s8, 3
	s_and_b32 s6, s3, -16
	v_bfi_b32 v44, -16, s3, v44
	v_readlane_b32 s3, v254, 3
	v_lshlrev_b32_e32 v53, 1, v52
	s_movk_i32 s7, 0x90
	v_lshlrev_b32_e32 v98, 4, v50
	v_or_b32_e32 v50, s9, v45
	v_mov_b32_e32 v56, s3
	v_mul_u32_u24_e32 v49, 0x90, v48
	v_mad_u32_u24 v48, v48, s7, v53
	v_mad_u32_u24 v99, v50, s7, v56
	s_ashr_i32 s7, s6, 31
	v_or_b32_e32 v54, s6, v51
	v_or_b32_e32 v51, s2, v51
	v_or_b32_e32 v52, s6, v52
	s_lshl_b64 s[2:3], s[6:7], 1
	v_readlane_b32 s6, v251, 49
	s_add_u32 s2, s6, s2
	v_readlane_b32 s6, v251, 50
	s_addc_u32 s3, s6, s3
	v_or_b32_e32 v55, 16, v50
	v_lshl_add_u32 v49, v52, 1, v49
	v_lshl_add_u64 v[88:89], s[2:3], 0, v[46:47]
	v_readlane_b32 s2, v254, 4
	v_or_b32_e32 v52, 2, v54
	v_mul_lo_u32 v1, v96, s99
	v_lshlrev_b32_e32 v200, 4, v44
	v_mul_lo_u32 v44, v44, s99
	v_lshlrev_b32_e32 v51, 1, v51
	v_add_u32_e32 v101, s2, v48
	v_cmp_gt_i32_e64 s[44:45], v52, v50
	v_cmp_gt_i32_e64 s[46:47], v52, v55
	v_or_b32_e32 v52, 3, v54
	v_readlane_b32 s3, v254, 5
	v_add_u32_e32 v102, s2, v49
	v_readlane_b32 s2, v254, 1
	v_readlane_b32 s6, v254, 6
	v_add_u32_e32 v1, 0, v1
	v_lshlrev_b32_e32 v100, 1, v54
	v_lshlrev_b32_e32 v46, 7, v96
	v_mad_u32_u24 v47, v50, s32, 0
	v_cmp_gt_i32_e64 s[36:37], v54, v50
	v_cmp_gt_i32_e64 s[38:39], v54, v55
	v_cmp_lt_i32_e64 s[40:41], v54, v50
	v_cmp_lt_i32_e64 s[42:43], v54, v55
	v_cmp_gt_i32_e64 s[48:49], v52, v50
	v_add_u32_e32 v50, s3, v51
	v_add_u32_e32 v54, s2, v44
	v_add_u32_e32 v103, s6, v48
	v_add_u32_e32 v48, s2, v51
	v_add_u32_e32 v104, s6, v49
	v_add_u32_e32 v49, s3, v44
	v_readlane_b32 s2, v251, 43
	v_add_u32_e32 v53, 0, v44
	v_add_u32_e32 v53, v53, v200
	v_add_u32_e32 v56, 0x900, v99
	v_sub_u32_e32 v46, v1, v46
	v_lshl_add_u32 v1, v96, 4, v1
	v_cmp_gt_i32_e64 s[50:51], v52, v55
	v_mul_u32_u24_e32 v52, 0x110, v45
	s_add_i32 s2, s2, s9
	v_mov_b32_e32 v44, 0
	v_add_u32_e32 v92, s2, v45
	s_mov_b32 s8, 0
	v_add_u32_e32 v105, v50, v52
	v_add_u32_e32 v106, v54, v98
	v_add_u32_e32 v107, v48, v52
	v_add_u32_e32 v108, v49, v98
	v_add_u32_e32 v2, v46, v2
	v_add_u32_e32 v109, v53, v98
	v_add_u32_e32 v110, v47, v98
	v_add_u32_e32 v111, v56, v100
	v_mov_b32_e32 v45, v44
	v_mov_b32_e32 v46, v44
	v_mov_b32_e32 v47, v44
	v_mov_b32_e32 v48, v44
	v_mov_b32_e32 v49, v44
	v_mov_b32_e32 v50, v44
	v_mov_b32_e32 v51, v44
	v_mov_b32_e32 v52, v44
	v_mov_b32_e32 v53, v44
	v_mov_b32_e32 v54, v44
	v_mov_b32_e32 v55, v44
	v_mov_b32_e32 v56, v44
	v_mov_b32_e32 v57, v44
	v_mov_b32_e32 v58, v44
	v_mov_b32_e32 v59, v44
	v_readlane_b32 s3, v251, 44
	s_branch .LBB0_115
; #define LAS __attribute__((address_space(3)))
; __device__ void gla_item(const Params& p, int item, LAS unsigned char* lds) {
;     ...
;         gla_wait(R, n2 == 0);
;         *(LAS u32x4*)(lds + qs + t * 272 + cgp * 32) = R.rq[0]; *(LAS u32x4*)(lds + qs + t * 272 + cgp * 32 + 16) = R.rq[1];
;         *(LAS u32x4*)(lds + KS + t * 272 + cgp * 32) = R.rk[0]; *(LAS u32x4*)(lds + KS + t * 272 + cgp * 32 + 16) = R.rk[1];
;         *(LAS u32x4*)(lds + vs + t * 144 + cgp * 16) = R.rv;
;         f32x4 dc; dc[0] = bflo(R.rdec.x); dc[1] = bfhi(R.rdec.x); dc[2] = bflo(R.rdec.y); dc[3] = bfhi(R.rdec.y);
;         asm volatile("" : "+v"(dc) :: "memory");
;         gla_load(R, (n + 2 < 64) ? n + 2 : 63, t, hq, hv, pdec);
;         LDS_BARRIER();
;         const unsigned kaddr = lbase + KS + (unsigned)((8 * g + (idx >> 2)) * 272 + (16 * w + 4 * (idx & 3)) * 2);
;         const unsigned vaddr = lbase + vs + (unsigned)((8 * g + (idx >> 2)) * 144 + (4 * (idx & 3)) * 2);
;         s16x4 k00, k01, k10, k11, a0, a1, a2, a3, b0, b1, b2, b3, c0, c1, c2, c3, d0, d1, d2, d3;
;         asm volatile(
;               "ds_read_b64_tr_b16 %0, %20\n\tds_read_b64_tr_b16 %1, %20 offset:1088\n\tds_read_b64_tr_b16 %2, %20 offset:8704\n\tds_read_b64_tr_b16 %3, %20 offset:9792\n\t"
;               "ds_read_b64_tr_b16 %4, %21\n\tds_read_b64_tr_b16 %5, %21 offset:32\n\tds_read_b64_tr_b16 %6, %21 offset:64\n\tds_read_b64_tr_b16 %7, %21 offset:96\n\t"
;               "ds_read_b64_tr_b16 %8, %21 offset:576\n\tds_read_b64_tr_b16 %9, %21 offset:608\n\tds_read_b64_tr_b16 %10, %21 offset:640\n\tds_read_b64_tr_b16 %11, %21 offset:672\n\t"
;               "ds_read_b64_tr_b16 %12, %21 offset:4608\n\tds_read_b64_tr_b16 %13, %21 offset:4640\n\tds_read_b64_tr_b16 %14, %21 offset:4672\n\tds_read_b64_tr_b16 %15, %21 offset:4704\n\t"
;               "ds_read_b64_tr_b16 %16, %21 offset:5184\n\tds_read_b64_tr_b16 %17, %21 offset:5216\n\tds_read_b64_tr_b16 %18, %21 offset:5248\n\tds_read_b64_tr_b16 %19, %21 offset:5280"
;               : "=&v"(k00), "=&v"(k01), "=&v"(k10), "=&v"(k11), "=&v"(a0), "=&v"(a1), "=&v"(a2), "=&v"(a3), "=&v"(b0), "=&v"(b1), "=&v"(b2), "=&v"(b3),
;                 "=&v"(c0), "=&v"(c1), "=&v"(c2), "=&v"(c3), "=&v"(d0), "=&v"(d1), "=&v"(d2), "=&v"(d3)
;               : "v"(kaddr), "v"(vaddr) : "memory");
;         { bf16x8 kf[4], qa[4], qb[4];
; #pragma unroll
.LBB0_114:
	s_add_i32 s2, s8, 1
	s_min_u32 s2, s2, 61
	s_lshl_b32 s2, s2, 6
	s_add_i32 s6, s2, 0x80
	ds_write_b128 v114, v[60:63] offset:18432
	ds_write_b128 v114, v[72:75] offset:18448
	ds_write_b128 v114, v[68:71] offset:36864
	ds_write_b128 v114, v[64:67] offset:36880
	ds_write_b128 v2, v[76:79] offset:64512
	v_lshlrev_b32_e32 v60, 16, v94
	v_and_b32_e32 v61, 0xffff0000, v94
	v_lshlrev_b32_e32 v62, 16, v95
	v_and_b32_e32 v63, 0xffff0000, v95
	v_add_u32_e32 v26, s6, v96
	s_movk_i32 s7, 0x3000
	s_lshl_b32 s18, s6, 10
	v_mad_i64_i32 v[36:37], s[2:3], v26, s7, v[80:81]
	v_lshl_add_u64 v[24:25], v[84:85], 0, s[18:19]
	v_lshl_add_u64 v[64:65], v[24:25], 0, s[12:13]
	v_mad_i64_i32 v[40:41], s[2:3], v26, s7, v[82:83]
	global_load_dwordx4 v[24:27], v[36:37], off
	v_lshl_add_u64 v[28:29], v[36:37], 0, 16
	global_load_dwordx4 v[28:31], v[28:29], off
	v_lshl_add_u64 v[32:33], v[36:37], 0, s[16:17]
	global_load_dwordx4 v[32:35], v[32:33], off
	v_lshl_add_u64 v[36:37], v[36:37], 0, s[22:23]
	global_load_dwordx4 v[36:39], v[36:37], off
	global_load_dwordx4 v[40:43], v[40:41], off
	global_load_dwordx2 v[90:91], v[64:65], off
	s_waitcnt lgkmcnt(0)
	s_barrier
	ds_read_b64_tr_b16 v[134:135], v97
	ds_read_b64_tr_b16 v[136:137], v97 offset:1152
	ds_read_b64_tr_b16 v[130:131], v97 offset:9216
	ds_read_b64_tr_b16 v[132:133], v97 offset:10368
	ds_read_b64_tr_b16 v[126:127], v103
	ds_read_b64_tr_b16 v[122:123], v103 offset:32
	ds_read_b64_tr_b16 v[118:119], v103 offset:64
	ds_read_b64_tr_b16 v[114:115], v103 offset:96
	ds_read_b64_tr_b16 v[128:129], v103 offset:576
	ds_read_b64_tr_b16 v[124:125], v103 offset:608
	ds_read_b64_tr_b16 v[120:121], v103 offset:640
	ds_read_b64_tr_b16 v[116:117], v103 offset:672
	ds_read_b64_tr_b16 v[76:77], v103 offset:4608
	ds_read_b64_tr_b16 v[72:73], v103 offset:4640
	ds_read_b64_tr_b16 v[68:69], v103 offset:4672
	ds_read_b64_tr_b16 v[64:65], v103 offset:4704
	ds_read_b64_tr_b16 v[78:79], v103 offset:5184
	ds_read_b64_tr_b16 v[74:75], v103 offset:5216
	ds_read_b64_tr_b16 v[70:71], v103 offset:5248
	ds_read_b64_tr_b16 v[66:67], v103 offset:5280
	ds_read_b128 v[138:141], v109 offset:36864
	ds_read_b128 v[168:171], v110 offset:18432
	ds_read_b128 v[172:175], v110 offset:23040
	ds_read_b128 v[150:153], v109 offset:36928
	s_waitcnt lgkmcnt(2)
	v_mfma_f32_16x16x32_bf16 v[142:145], v[138:141], v[168:171], 0
	s_add_i32 s2, s8, 2
	s_cmp_lt_u32 s8, 62
	s_mov_b32 s8, s2
	s_waitcnt lgkmcnt(1)
	v_mfma_f32_16x16x32_bf16 v[138:141], v[138:141], v[172:175], 0
	ds_read_b128 v[176:179], v110 offset:18496
	ds_read_b128 v[180:183], v110 offset:23104
	s_waitcnt lgkmcnt(1)
	v_mfma_f32_16x16x32_bf16 v[142:145], v[150:153], v[176:179], v[142:145]
	ds_read_b128 v[146:149], v109 offset:36992
	s_waitcnt lgkmcnt(1)
	v_mfma_f32_16x16x32_bf16 v[138:141], v[150:153], v[180:183], v[138:141]
	ds_read_b128 v[184:187], v110 offset:18560
	ds_read_b128 v[188:191], v110 offset:23168
	s_waitcnt lgkmcnt(1)
	v_mfma_f32_16x16x32_bf16 v[142:145], v[146:149], v[184:187], v[142:145]
	ds_read_b128 v[150:153], v109 offset:37056
	s_waitcnt lgkmcnt(1)
	v_mfma_f32_16x16x32_bf16 v[138:141], v[146:149], v[188:191], v[138:141]
	ds_read_b128 v[192:195], v110 offset:18624
	s_waitcnt lgkmcnt(0)
	v_mfma_f32_16x16x32_bf16 v[142:145], v[150:153], v[192:195], v[142:145]
	ds_read_b128 v[196:199], v110 offset:23232
	s_waitcnt lgkmcnt(0)
	s_nop 0
	v_mfma_f32_16x16x32_bf16 v[56:59], v[134:137], v[126:129], v[56:59]
	s_nop 4
	v_cndmask_b32_e64 v93, v142, 0, s[36:37]
	v_cndmask_b32_e64 v95, v145, 0, s[48:49]
	v_mfma_f32_16x16x32_bf16 v[52:55], v[134:137], v[122:125], v[52:55]
	v_mfma_f32_16x16x32_bf16 v[48:51], v[134:137], v[118:121], v[48:51]
	v_mfma_f32_16x16x32_bf16 v[44:47], v[134:137], v[114:117], v[44:47]
	v_mfma_f32_16x16x32_bf16 v[56:59], v[130:133], v[76:79], v[56:59]
	v_cndmask_b32_e64 v76, 0, v143, s[40:41]
	v_cndmask_b32_e64 v78, v144, 0, s[44:45]
	s_waitcnt lgkmcnt(0)
	v_mfma_f32_16x16x32_bf16 v[138:141], v[150:153], v[196:199], v[138:141]
	v_mfma_f32_16x16x32_bf16 v[52:55], v[130:133], v[72:75], v[52:55]
	s_nop 2
	v_mul_f32_e64 v58, v62, v58
	v_mul_f32_e64 v59, v63, v59
	v_pk_mul_f32 v[56:57], v[60:61], v[56:57]
	s_nop 0
	v_cndmask_b32_e64 v94, v138, 0, s[38:39]
	v_mfma_f32_16x16x32_bf16 v[48:51], v[130:133], v[68:71], v[48:51]
	v_cndmask_b32_e64 v77, 0, v139, s[42:43]
	v_cndmask_b32_e64 v79, v140, 0, s[46:47]
	v_cndmask_b32_e64 v122, v141, 0, s[50:51]
	v_mfma_f32_16x16x32_bf16 v[44:47], v[130:133], v[64:67], v[44:47]
	v_cvt_pk_bf16_f32 v72, v93, v76
	v_cvt_pk_bf16_f32 v73, v78, v95
	v_pk_mul_f32 v[54:55], v[62:63], v[54:55]
	v_pk_mul_f32 v[52:53], v[60:61], v[52:53]
	v_pk_mul_f32 v[48:49], v[60:61], v[48:49]
	s_nop 2
	v_pk_mul_f32 v[44:45], v[60:61], v[44:45]
	v_cvt_pk_bf16_f32 v60, v56, v57
	v_cvt_pk_bf16_f32 v61, v58, v59
	v_cvt_pk_bf16_f32 v74, v94, v77
	v_cvt_pk_bf16_f32 v75, v79, v122
	ds_write_b64 v113, v[72:73]
	ds_write_b64 v111, v[74:75]
	v_pk_mul_f32 v[50:51], v[62:63], v[50:51]
	ds_write_b64 v107, v[60:61]
	v_cvt_pk_bf16_f32 v60, v52, v53
	v_cvt_pk_bf16_f32 v61, v54, v55
	v_pk_mul_f32 v[46:47], v[62:63], v[46:47]
	ds_write_b64 v107, v[60:61] offset:4352
	v_cvt_pk_bf16_f32 v60, v48, v49
	v_cvt_pk_bf16_f32 v61, v50, v51
	ds_write_b64 v107, v[60:61] offset:8704
	v_cvt_pk_bf16_f32 v60, v44, v45
	v_cvt_pk_bf16_f32 v61, v46, v47
	ds_write_b64 v107, v[60:61] offset:13056
	s_waitcnt lgkmcnt(0)
	s_barrier
; __device__ __forceinline__ unsigned cvt_pk_bf16(float lo, float hi) { const f32x2v v = {lo, hi}; const b16x2v r = __builtin_convertvector(v, b16x2v); return __builtin_bit_cast(unsigned, r); }
; __device__ __forceinline__ f32x4 mfma16(bf16x8 a, bf16x8 b, f32x4 c) { return __builtin_amdgcn_mfma_f32_16x16x32_bf16(a, b, c, 0, 0, 0); }
; __device__ void gla_item(const Params& p, int item, LAS unsigned char* lds) {
;     ...
;         { const unsigned va = lbase + vs + (unsigned)((8 * g + (idx >> 2)) * 144 + (16 * jt + 4 * (idx & 3)) * 2);
;           s16x4 x0, x1, y0, y1;
;           asm volatile("ds_read_b64_tr_b16 %0, %4\n\tds_read_b64_tr_b16 %1, %4 offset:576\n\tds_read_b64_tr_b16 %2, %4 offset:4608\n\tds_read_b64_tr_b16 %3, %4 offset:5184"
;                        : "=&v"(x0), "=&v"(x1), "=&v"(y0), "=&v"(y1) : "v"(va) : "memory");
;           bf16x8 sf[4], qa[4], qb[4], a0f[2], a1f[2];
; #pragma unroll
;           for (int ks = 0; ks < 4; ++ks) { sf[ks] = frag_row(lds + stc, 272, 16 * jt, 32 * ks, idx, g); qa[ks] = frag_row(lds + qs, 272, 16 * it0, 32 * ks, idx, g); qb[ks] = frag_row(lds + qs, 272, 16 * it0 + 16, 32 * ks, idx, g); }
; #pragma unroll
;           for (int ks = 0; ks < 2; ++ks) { a0f[ks] = frag_row(lds + AS, 144, 16 * it0, 32 * ks, idx, g); a1f[ks] = frag_row(lds + AS, 144, 16 * it0 + 16, 32 * ks, idx, g); }
;           asm volatile("s_waitcnt lgkmcnt(0)" : "+v"(x0), "+v"(x1), "+v"(y0), "+v"(y1) :: "memory");
;           bf16x8 vf0, vf1;
;           MKF(vf0, x0, x1) MKF(vf1, y0, y1)
;           f32x4 oa = {0.f, 0.f, 0.f, 0.f}, ob = oa;
;           oa = mfma16(vf0, a0f[0], oa); ob = mfma16(vf0, a1f[0], ob); oa = mfma16(vf1, a0f[1], oa); ob = mfma16(vf1, a1f[1], ob);
; #pragma unroll
;           for (int ks = 0; ks < 4; ++ks) { oa = mfma16(sf[ks], qa[ks], oa); ob = mfma16(sf[ks], qb[ks], ob); }
;           u32x2 wa, wb; wa.x = cvt_pk_bf16(oa[0], oa[1]); wa.y = cvt_pk_bf16(oa[2], oa[3]); wb.x = cvt_pk_bf16(ob[0], ob[1]); wb.y = cvt_pk_bf16(ob[2], ob[3]);
;           bf16_t* op = og + (size_t)(b * SEQ + n * 64 + 16 * it0 + idx) * 1024 + hh * 256 + sl * 64 + 16 * jt + 4 * g;
;           *(u32x2*)op = wa; *(u32x2*)(op + 16 * 1024) = wb; }
	ds_read_b64_tr_b16 v[64:65], v104
	ds_read_b64_tr_b16 v[66:67], v104 offset:576
	ds_read_b64_tr_b16 v[60:61], v104 offset:4608
	ds_read_b64_tr_b16 v[62:63], v104 offset:5184
	ds_read_b128 v[68:71], v108
	ds_read_b128 v[72:75], v108 offset:64
	ds_read_b128 v[126:129], v108 offset:128
	ds_read_b128 v[130:133], v108 offset:192
	ds_read_b128 v[150:153], v112
	ds_read_b128 v[154:157], v112 offset:64
	ds_read_b128 v[158:161], v112 offset:2304
	ds_read_b128 v[162:165], v112 offset:2368
	s_waitcnt lgkmcnt(0)
	s_waitcnt lgkmcnt(3)
	v_mfma_f32_16x16x32_bf16 v[150:153], v[64:67], v[150:153], 0
	s_waitcnt lgkmcnt(1)
	v_mfma_f32_16x16x32_bf16 v[64:67], v[64:67], v[158:161], 0
	v_mfma_f32_16x16x32_bf16 v[150:153], v[60:63], v[154:157], v[150:153]
	s_waitcnt lgkmcnt(0)
	v_mfma_f32_16x16x32_bf16 v[60:63], v[60:63], v[162:165], v[64:67]
	v_mfma_f32_16x16x32_bf16 v[60:63], v[68:71], v[172:175], v[60:63]
	v_mfma_f32_16x16x32_bf16 v[64:67], v[68:71], v[168:171], v[150:153]
	v_mfma_f32_16x16x32_bf16 v[60:63], v[72:75], v[180:183], v[60:63]
	v_mfma_f32_16x16x32_bf16 v[64:67], v[72:75], v[176:179], v[64:67]
	v_mfma_f32_16x16x32_bf16 v[60:63], v[126:129], v[188:191], v[60:63]
	v_mfma_f32_16x16x32_bf16 v[64:67], v[126:129], v[184:187], v[64:67]
	v_mfma_f32_16x16x32_bf16 v[60:63], v[130:133], v[196:199], v[60:63]
	v_mfma_f32_16x16x32_bf16 v[64:67], v[130:133], v[192:195], v[64:67]
	s_nop 6
	v_cvt_pk_bf16_f32 v60, v60, v61
	v_cvt_pk_bf16_f32 v61, v62, v63
	v_add_u32_e32 v62, 64, v92
	v_ashrrev_i32_e32 v63, 31, v62
	v_lshlrev_b64 v[62:63], 11, v[62:63]
	v_cvt_pk_bf16_f32 v64, v64, v65
	v_cvt_pk_bf16_f32 v65, v66, v67
	v_lshl_add_u64 v[62:63], v[88:89], 0, v[62:63]
	global_store_dwordx2 v[62:63], v[64:65], off
	v_add_co_u32_e32 v62, vcc, 0x8000, v62
	v_add_u32_e32 v92, 0x80, v92
	s_nop 0
	v_addc_co_u32_e32 v63, vcc, 0, v63, vcc
	global_store_dwordx2 v[62:63], v[60:61], off
	s_cbranch_scc0 .LBB0_128

; #define LAS __attribute__((address_space(3)))
; __device__ void gla_item(const Params& p, int item, LAS unsigned char* lds) {
;     ...
;         *(LAS u32x4*)(lds + qs + t * 272 + cgp * 32) = R.rq[0]; *(LAS u32x4*)(lds + qs + t * 272 + cgp * 32 + 16) = R.rq[1];
;         *(LAS u32x4*)(lds + KS + t * 272 + cgp * 32) = R.rk[0]; *(LAS u32x4*)(lds + KS + t * 272 + cgp * 32 + 16) = R.rk[1];
;         *(LAS u32x4*)(lds + vs + t * 144 + cgp * 16) = R.rv;
;         f32x4 dc; dc[0] = bflo(R.rdec.x); dc[1] = bfhi(R.rdec.x); dc[2] = bflo(R.rdec.y); dc[3] = bfhi(R.rdec.y);
;         asm volatile("" : "+v"(dc) :: "memory");
;         gla_load(R, (n + 2 < 64) ? n + 2 : 63, t, hq, hv, pdec);
;         LDS_BARRIER();
;         const unsigned kaddr = lbase + KS + (unsigned)((8 * g + (idx >> 2)) * 272 + (16 * w + 4 * (idx & 3)) * 2);
;         const unsigned vaddr = lbase + vs + (unsigned)((8 * g + (idx >> 2)) * 144 + (4 * (idx & 3)) * 2);
;         s16x4 k00, k01, k10, k11, a0, a1, a2, a3, b0, b1, b2, b3, c0, c1, c2, c3, d0, d1, d2, d3;
;         asm volatile(
;               "ds_read_b64_tr_b16 %0, %20\n\tds_read_b64_tr_b16 %1, %20 offset:1088\n\tds_read_b64_tr_b16 %2, %20 offset:8704\n\tds_read_b64_tr_b16 %3, %20 offset:9792\n\t"
;               "ds_read_b64_tr_b16 %4, %21\n\tds_read_b64_tr_b16 %5, %21 offset:32\n\tds_read_b64_tr_b16 %6, %21 offset:64\n\tds_read_b64_tr_b16 %7, %21 offset:96\n\t"
;               "ds_read_b64_tr_b16 %8, %21 offset:576\n\tds_read_b64_tr_b16 %9, %21 offset:608\n\tds_read_b64_tr_b16 %10, %21 offset:640\n\tds_read_b64_tr_b16 %11, %21 offset:672\n\t"
;               "ds_read_b64_tr_b16 %12, %21 offset:4608\n\tds_read_b64_tr_b16 %13, %21 offset:4640\n\tds_read_b64_tr_b16 %14, %21 offset:4672\n\tds_read_b64_tr_b16 %15, %21 offset:4704\n\t"
;               "ds_read_b64_tr_b16 %16, %21 offset:5184\n\tds_read_b64_tr_b16 %17, %21 offset:5216\n\tds_read_b64_tr_b16 %18, %21 offset:5248\n\tds_read_b64_tr_b16 %19, %21 offset:5280"
;               : "=&v"(k00), "=&v"(k01), "=&v"(k10), "=&v"(k11), "=&v"(a0), "=&v"(a1), "=&v"(a2), "=&v"(a3), "=&v"(b0), "=&v"(b1), "=&v"(b2), "=&v"(b3),
;                 "=&v"(c0), "=&v"(c1), "=&v"(c2), "=&v"(c3), "=&v"(d0), "=&v"(d1), "=&v"(d2), "=&v"(d3)
;               : "v"(kaddr), "v"(vaddr) : "memory");
;         { bf16x8 kf[4], qa[4], qb[4];
; #pragma unroll
.LBB0_118:
	s_min_u32 s6, s8, 61
	s_lshl_b32 s6, s6, 6
	v_add_u32_e32 v114, v1, v0
	s_add_i32 s9, s6, 0x80
	ds_write_b128 v114, v[64:67]
	ds_write_b128 v114, v[60:63] offset:16
	ds_write_b128 v114, v[76:79] offset:36864
	ds_write_b128 v114, v[72:75] offset:36880
	ds_write_b128 v2, v[68:71] offset:55296
	v_lshlrev_b32_e32 v60, 16, v94
	v_and_b32_e32 v61, 0xffff0000, v94
	v_lshlrev_b32_e32 v62, 16, v95
	v_and_b32_e32 v63, 0xffff0000, v95
	v_add_u32_e32 v6, s9, v96
	s_movk_i32 s10, 0x3000
	s_lshl_b32 s18, s9, 10
	v_mad_i64_i32 v[16:17], s[6:7], v6, s10, v[80:81]
	v_lshl_add_u64 v[4:5], v[84:85], 0, s[18:19]
	v_lshl_add_u64 v[64:65], v[4:5], 0, s[12:13]
	v_mad_i64_i32 v[20:21], s[6:7], v6, s10, v[82:83]
	global_load_dwordx4 v[4:7], v[16:17], off
	v_lshl_add_u64 v[8:9], v[16:17], 0, 16
	global_load_dwordx4 v[8:11], v[8:9], off
	v_lshl_add_u64 v[12:13], v[16:17], 0, s[16:17]
	global_load_dwordx4 v[12:15], v[12:13], off
	v_lshl_add_u64 v[16:17], v[16:17], 0, s[22:23]
	global_load_dwordx4 v[16:19], v[16:17], off
	global_load_dwordx4 v[20:23], v[20:21], off
	global_load_dwordx2 v[86:87], v[64:65], off
	s_waitcnt lgkmcnt(0)
	s_barrier
	ds_read_b64_tr_b16 v[136:137], v97
	ds_read_b64_tr_b16 v[138:139], v97 offset:1152
	ds_read_b64_tr_b16 v[132:133], v97 offset:9216
	ds_read_b64_tr_b16 v[134:135], v97 offset:10368
	ds_read_b64_tr_b16 v[128:129], v101
	ds_read_b64_tr_b16 v[124:125], v101 offset:32
	ds_read_b64_tr_b16 v[120:121], v101 offset:64
	ds_read_b64_tr_b16 v[116:117], v101 offset:96
	ds_read_b64_tr_b16 v[130:131], v101 offset:576
	ds_read_b64_tr_b16 v[126:127], v101 offset:608
	ds_read_b64_tr_b16 v[122:123], v101 offset:640
	ds_read_b64_tr_b16 v[118:119], v101 offset:672
	ds_read_b64_tr_b16 v[76:77], v101 offset:4608
	ds_read_b64_tr_b16 v[72:73], v101 offset:4640
	ds_read_b64_tr_b16 v[68:69], v101 offset:4672
	ds_read_b64_tr_b16 v[64:65], v101 offset:4704
	ds_read_b64_tr_b16 v[78:79], v101 offset:5184
	ds_read_b64_tr_b16 v[74:75], v101 offset:5216
	ds_read_b64_tr_b16 v[70:71], v101 offset:5248
	ds_read_b64_tr_b16 v[66:67], v101 offset:5280
	ds_read_b128 v[140:143], v109 offset:36864
	ds_read_b128 v[168:171], v110
	ds_read_b128 v[148:151], v109 offset:36928
	ds_read_b128 v[172:175], v110 offset:64
	s_waitcnt lgkmcnt(0)
	v_mfma_f32_16x16x32_bf16 v[144:147], v[140:143], v[168:171], 0
	ds_read_b128 v[176:179], v110 offset:4608
	ds_read_b128 v[180:183], v110 offset:4672
	v_mfma_f32_16x16x32_bf16 v[144:147], v[148:151], v[172:175], v[144:147]
	ds_read_b128 v[152:155], v109 offset:36992
	s_waitcnt lgkmcnt(2)
	v_mfma_f32_16x16x32_bf16 v[140:143], v[140:143], v[176:179], 0
	s_waitcnt lgkmcnt(1)
	v_mfma_f32_16x16x32_bf16 v[140:143], v[148:151], v[180:183], v[140:143]
	ds_read_b128 v[184:187], v110 offset:128
	ds_read_b128 v[156:159], v109 offset:37056
	ds_read_b128 v[188:191], v110 offset:192
	s_waitcnt lgkmcnt(2)
	v_mfma_f32_16x16x32_bf16 v[144:147], v[152:155], v[184:187], v[144:147]
	ds_read_b128 v[192:195], v110 offset:4736
	ds_read_b128 v[196:199], v110 offset:4800
	s_waitcnt lgkmcnt(0)
	s_waitcnt lgkmcnt(1)
	v_mfma_f32_16x16x32_bf16 v[140:143], v[152:155], v[192:195], v[140:143]
	v_mfma_f32_16x16x32_bf16 v[56:59], v[136:139], v[128:131], v[56:59]
	v_mfma_f32_16x16x32_bf16 v[52:55], v[136:139], v[124:127], v[52:55]
	v_mfma_f32_16x16x32_bf16 v[48:51], v[136:139], v[120:123], v[48:51]
	v_mfma_f32_16x16x32_bf16 v[44:47], v[136:139], v[116:119], v[44:47]
	v_mfma_f32_16x16x32_bf16 v[144:147], v[156:159], v[188:191], v[144:147]
	s_waitcnt lgkmcnt(0)
	v_mfma_f32_16x16x32_bf16 v[140:143], v[156:159], v[196:199], v[140:143]
	v_mfma_f32_16x16x32_bf16 v[56:59], v[132:135], v[76:79], v[56:59]
	s_nop 4
	v_cndmask_b32_e64 v93, v144, 0, s[36:37]
	v_cndmask_b32_e64 v95, 0, v145, s[40:41]
	v_cndmask_b32_e64 v77, v146, 0, s[44:45]
	v_mfma_f32_16x16x32_bf16 v[52:55], v[132:135], v[72:75], v[52:55]
	v_cndmask_b32_e64 v79, v142, 0, s[46:47]
	v_cndmask_b32_e64 v112, v147, 0, s[48:49]
	v_cndmask_b32_e64 v113, v143, 0, s[50:51]
	v_mfma_f32_16x16x32_bf16 v[48:51], v[132:135], v[68:71], v[48:51]
	v_mul_f32_e64 v58, v62, v58
	v_mul_f32_e64 v59, v63, v59
	v_pk_mul_f32 v[56:57], v[60:61], v[56:57]
	v_cndmask_b32_e64 v94, v140, 0, s[38:39]
	v_mfma_f32_16x16x32_bf16 v[44:47], v[132:135], v[64:67], v[44:47]
	v_cndmask_b32_e64 v78, 0, v141, s[42:43]
	v_cvt_pk_bf16_f32 v76, v93, v95
	v_cvt_pk_bf16_f32 v77, v77, v112
	v_cvt_pk_bf16_f32 v73, v79, v113
	v_add_u32_e32 v113, v99, v100
	v_pk_mul_f32 v[54:55], v[62:63], v[54:55]
	v_pk_mul_f32 v[52:53], v[60:61], v[52:53]
	v_pk_mul_f32 v[48:49], v[60:61], v[48:49]
	v_pk_mul_f32 v[44:45], v[60:61], v[44:45]
	v_cvt_pk_bf16_f32 v60, v56, v57
	v_cvt_pk_bf16_f32 v61, v58, v59
	v_cvt_pk_bf16_f32 v72, v94, v78
	ds_write_b64 v113, v[76:77]
	ds_write_b64 v111, v[72:73]
	v_pk_mul_f32 v[50:51], v[62:63], v[50:51]
	ds_write_b64 v105, v[60:61]
	v_cvt_pk_bf16_f32 v60, v52, v53
	v_cvt_pk_bf16_f32 v61, v54, v55
	v_pk_mul_f32 v[46:47], v[62:63], v[46:47]
	ds_write_b64 v105, v[60:61] offset:4352
	v_cvt_pk_bf16_f32 v60, v48, v49
	v_cvt_pk_bf16_f32 v61, v50, v51
	ds_write_b64 v105, v[60:61] offset:8704
	v_cvt_pk_bf16_f32 v60, v44, v45
	v_cvt_pk_bf16_f32 v61, v46, v47
	ds_write_b64 v105, v[60:61] offset:13056
	s_waitcnt lgkmcnt(0)
	s_barrier
; __device__ __forceinline__ unsigned cvt_pk_bf16(float lo, float hi) { const f32x2v v = {lo, hi}; const b16x2v r = __builtin_convertvector(v, b16x2v); return __builtin_bit_cast(unsigned, r); }
; __device__ __forceinline__ f32x4 mfma16(bf16x8 a, bf16x8 b, f32x4 c) { return __builtin_amdgcn_mfma_f32_16x16x32_bf16(a, b, c, 0, 0, 0); }
; __device__ void gla_item(const Params& p, int item, LAS unsigned char* lds) {
;     ...
;         { const unsigned va = lbase + vs + (unsigned)((8 * g + (idx >> 2)) * 144 + (16 * jt + 4 * (idx & 3)) * 2);
;           s16x4 x0, x1, y0, y1;
;           asm volatile("ds_read_b64_tr_b16 %0, %4\n\tds_read_b64_tr_b16 %1, %4 offset:576\n\tds_read_b64_tr_b16 %2, %4 offset:4608\n\tds_read_b64_tr_b16 %3, %4 offset:5184"
;                        : "=&v"(x0), "=&v"(x1), "=&v"(y0), "=&v"(y1) : "v"(va) : "memory");
;           bf16x8 sf[4], qa[4], qb[4], a0f[2], a1f[2];
; #pragma unroll
;           for (int ks = 0; ks < 4; ++ks) { sf[ks] = frag_row(lds + stc, 272, 16 * jt, 32 * ks, idx, g); qa[ks] = frag_row(lds + qs, 272, 16 * it0, 32 * ks, idx, g); qb[ks] = frag_row(lds + qs, 272, 16 * it0 + 16, 32 * ks, idx, g); }
; #pragma unroll
;           for (int ks = 0; ks < 2; ++ks) { a0f[ks] = frag_row(lds + AS, 144, 16 * it0, 32 * ks, idx, g); a1f[ks] = frag_row(lds + AS, 144, 16 * it0 + 16, 32 * ks, idx, g); }
;           asm volatile("s_waitcnt lgkmcnt(0)" : "+v"(x0), "+v"(x1), "+v"(y0), "+v"(y1) :: "memory");
;           bf16x8 vf0, vf1;
;           MKF(vf0, x0, x1) MKF(vf1, y0, y1)
;           f32x4 oa = {0.f, 0.f, 0.f, 0.f}, ob = oa;
;           oa = mfma16(vf0, a0f[0], oa); ob = mfma16(vf0, a1f[0], ob); oa = mfma16(vf1, a0f[1], oa); ob = mfma16(vf1, a1f[1], ob);
; #pragma unroll
;           for (int ks = 0; ks < 4; ++ks) { oa = mfma16(sf[ks], qa[ks], oa); ob = mfma16(sf[ks], qb[ks], ob); }
;           u32x2 wa, wb; wa.x = cvt_pk_bf16(oa[0], oa[1]); wa.y = cvt_pk_bf16(oa[2], oa[3]); wb.x = cvt_pk_bf16(ob[0], ob[1]); wb.y = cvt_pk_bf16(ob[2], ob[3]);
;           bf16_t* op = og + (size_t)(b * SEQ + n * 64 + 16 * it0 + idx) * 1024 + hh * 256 + sl * 64 + 16 * jt + 4 * g;
;           *(u32x2*)op = wa; *(u32x2*)(op + 16 * 1024) = wb; }
	ds_read_b64_tr_b16 v[64:65], v102
	ds_read_b64_tr_b16 v[66:67], v102 offset:576
	ds_read_b64_tr_b16 v[60:61], v102 offset:4608
	ds_read_b64_tr_b16 v[62:63], v102 offset:5184
	v_add_u32_e32 v112, v99, v98
	ds_read_b128 v[68:71], v106
	ds_read_b128 v[72:75], v106 offset:64
	ds_read_b128 v[128:131], v106 offset:128
	ds_read_b128 v[132:135], v106 offset:192
	ds_read_b128 v[152:155], v112
	ds_read_b128 v[156:159], v112 offset:64
	ds_read_b128 v[160:163], v112 offset:2304
	ds_read_b128 v[164:167], v112 offset:2368
	s_waitcnt lgkmcnt(0)
	v_ashrrev_i32_e32 v93, 31, v92
	s_waitcnt lgkmcnt(3)
	v_mfma_f32_16x16x32_bf16 v[152:155], v[64:67], v[152:155], 0
	s_waitcnt lgkmcnt(1)
	v_mfma_f32_16x16x32_bf16 v[64:67], v[64:67], v[160:163], 0
	v_mfma_f32_16x16x32_bf16 v[152:155], v[60:63], v[156:159], v[152:155]
	s_waitcnt lgkmcnt(0)
	v_mfma_f32_16x16x32_bf16 v[60:63], v[60:63], v[164:167], v[64:67]
	v_mfma_f32_16x16x32_bf16 v[60:63], v[68:71], v[176:179], v[60:63]
	v_mfma_f32_16x16x32_bf16 v[64:67], v[68:71], v[168:171], v[152:155]
	v_mfma_f32_16x16x32_bf16 v[60:63], v[72:75], v[180:183], v[60:63]
	v_mfma_f32_16x16x32_bf16 v[64:67], v[72:75], v[172:175], v[64:67]
	v_mfma_f32_16x16x32_bf16 v[60:63], v[128:131], v[192:195], v[60:63]
	v_mfma_f32_16x16x32_bf16 v[64:67], v[128:131], v[184:187], v[64:67]
	v_mfma_f32_16x16x32_bf16 v[60:63], v[132:135], v[196:199], v[60:63]
	v_mfma_f32_16x16x32_bf16 v[64:67], v[132:135], v[188:191], v[64:67]
	s_nop 6
	v_cvt_pk_bf16_f32 v60, v60, v61
	v_cvt_pk_bf16_f32 v61, v62, v63
	v_lshlrev_b64 v[62:63], 11, v[92:93]
	v_cvt_pk_bf16_f32 v64, v64, v65
	v_cvt_pk_bf16_f32 v65, v66, v67
	v_lshl_add_u64 v[62:63], v[88:89], 0, v[62:63]
	global_store_dwordx2 v[62:63], v[64:65], off
	v_add_co_u32_e32 v62, vcc, 0x8000, v62
	s_nop 1
	v_addc_co_u32_e32 v63, vcc, 0, v63, vcc
	s_andn2_b64 vcc, exec, s[2:3]
	global_store_dwordx2 v[62:63], v[60:61], off
	s_cbranch_vccnz .LBB0_121
	v_mov_b64_e32 v[66:67], v[38:39]
	v_mov_b64_e32 v[62:63], v[26:27]
	v_mov_b64_e32 v[70:71], v[34:35]
	v_mov_b64_e32 v[78:79], v[42:43]
	v_mov_b64_e32 v[74:75], v[30:31]
	v_mov_b64_e32 v[64:65], v[36:37]
	v_mov_b64_e32 v[94:95], v[90:91]
	v_mov_b64_e32 v[60:61], v[24:25]
	v_mov_b64_e32 v[68:69], v[32:33]
	v_mov_b64_e32 v[76:77], v[40:41]
	v_mov_b64_e32 v[72:73], v[28:29]
	s_waitcnt vmcnt(10)
	s_cbranch_execnz .LBB0_114
	s_branch .LBB0_122
